# attention q/k projection epilogue: rope-table loads of the wc==0 waves hoisted and kept in flight (counted vmcnt), waves without loads no longer wait for their own stores
# speedup vs baseline: 1.0012x; 1.0012x over previous
; __device__ __forceinline__ unsigned cvt_pk_bf16(float lo, float hi) { unsigned r; asm volatile("v_cvt_pk_bf16_f32 %0, %1, %2" : "=v"(r) : "v"(lo), "v"(hi)); return r; }
;     __device__ __forceinline__ void operator()(const Acc& acc, const Unit& u, int wr, int wc, int fr, int fq) const {
;     ...
;                 const int row_in = ai * HALF + wr * 64 + m * 16 + fr, c = u.pm * BM + row_in;
;                 const int tok = ((c & ((1 << lL) - 1)) << ld) + (c >> lL);
;                 f32x4 t0 = (f32x4){1.f, 0.f, 1.f, 0.f}, t1 = t0;
;                 if (wc == 0) { const f32x4* cp = csa + ((size_t)tok * 16 + 4 * fq) / 2; t0 = cp[0]; t1 = cp[1]; }
;                 bf16_t* rowp = O + u.coff + (size_t)row_in * D + wc * 32 + ((fq & 1) ? 16 + 4 * (fq - 1) : 4 * fq);
; #pragma unroll
;                 for (int bj = 0; bj < 2; ++bj) {
;                     const f32x4 x1 = acc[ai][bj][m][0], x2 = acc[ai][bj][m][1];
;                     float o1[4], o2[4];
;                     const float cc[4] = {t0[0], t0[2], t1[0], t1[2]}, ss[4] = {t0[1], t0[3], t1[1], t1[3]};
; #pragma unroll
;                     for (int j = 0; j < 4; ++j) { o1[j] = x1[j] * cc[j] - x2[j] * ss[j]; o2[j] = x2[j] * cc[j] + x1[j] * ss[j]; }
;                     const unsigned lo0 = cvt_pk_bf16(o1[0], o1[1]), lo1 = cvt_pk_bf16(o1[2], o1[3]), hi0 = cvt_pk_bf16(o2[0], o2[1]), hi1 = cvt_pk_bf16(o2[2], o2[3]);
;                     const auto s0 = __builtin_amdgcn_permlane16_swap(lo0, hi0, false, false), s1 = __builtin_amdgcn_permlane16_swap(lo1, hi1, false, false);
;                     *(u32x4*)(rowp + bj * HALF) = (u32x4){s0[0], s1[0], s0[1], s1[1]};
.LBB0_226:
	v_mov_b32_e32 v165, v169
	v_mov_b32_e32 v128, v168
	v_cndmask_b32_e64 v130, 0, 1, s[30:31]
	v_lshlrev_b32_e32 v162, 2, v165
	v_add_u32_e32 v164, s13, v128
	s_lshl_b32 s46, s45, 8
	v_ashrrev_i32_e32 v163, 31, v162
	v_mov_b32_e32 v129, 0
	v_mov_b32_e32 v128, 1.0
	v_cmp_ne_u32_e64 s[42:43], 1, v130
	s_andn2_b64 vcc, exec, s[30:31]
	v_mov_b32_e32 v130, 1.0
	v_mov_b32_e32 v131, 0
	v_mov_b32_e32 v132, 1.0
	v_mov_b32_e32 v133, 0
	v_mov_b32_e32 v134, 1.0
	v_mov_b32_e32 v135, 0
	v_mov_b32_e32 v136, 1.0
	v_mov_b32_e32 v137, 0
	s_cbranch_vccnz .LBB0_228
	v_add_u32_e32 v196, s46, v164
	v_lshlrev_b32_e32 v197, s1, v196
	v_and_b32_e32 v197, 0x3fff, v197
	v_ashrrev_i32_e32 v196, s10, v196
	v_add_u32_e32 v196, v197, v196
	v_ashrrev_i32_e32 v197, 31, v196
	v_lshl_add_u64 v[196:197], v[196:197], 4, v[162:163]
	v_lshl_add_u64 v[196:197], v[196:197], 3, s[18:19]
	global_load_dwordx4 v[192:195], v[196:197], off offset:16
	s_nop 0
	global_load_dwordx4 v[196:199], v[196:197], off
	v_add_u32_e32 v204, 16, v164
	v_add_u32_e32 v204, s46, v204
	v_lshlrev_b32_e32 v205, s1, v204
	v_and_b32_e32 v205, 0x3fff, v205
	v_ashrrev_i32_e32 v204, s10, v204
	v_add_u32_e32 v204, v205, v204
	v_ashrrev_i32_e32 v205, 31, v204
	v_lshl_add_u64 v[204:205], v[204:205], 4, v[162:163]
	v_lshl_add_u64 v[204:205], v[204:205], 3, s[18:19]
	global_load_dwordx4 v[200:203], v[204:205], off offset:16
	s_nop 0
	global_load_dwordx4 v[204:207], v[204:205], off
	v_add_u32_e32 v212, 32, v164
	v_add_u32_e32 v212, s46, v212
	v_lshlrev_b32_e32 v213, s1, v212
	v_and_b32_e32 v213, 0x3fff, v213
	v_ashrrev_i32_e32 v212, s10, v212
	v_add_u32_e32 v212, v213, v212
	v_ashrrev_i32_e32 v213, 31, v212
	v_lshl_add_u64 v[212:213], v[212:213], 4, v[162:163]
	v_lshl_add_u64 v[212:213], v[212:213], 3, s[18:19]
	global_load_dwordx4 v[208:211], v[212:213], off offset:16
	s_nop 0
	global_load_dwordx4 v[212:215], v[212:213], off
	v_add_u32_e32 v220, 48, v164
	v_add_u32_e32 v220, s46, v220
	v_lshlrev_b32_e32 v221, s1, v220
	v_and_b32_e32 v221, 0x3fff, v221
	v_ashrrev_i32_e32 v220, s10, v220
	v_add_u32_e32 v220, v221, v220
	v_ashrrev_i32_e32 v221, 31, v220
	v_lshl_add_u64 v[220:221], v[220:221], 4, v[162:163]
	v_lshl_add_u64 v[220:221], v[220:221], 3, s[18:19]
	global_load_dwordx4 v[216:219], v[220:221], off offset:16
	s_nop 0
	global_load_dwordx4 v[220:223], v[220:221], off
	v_add_u32_e32 v228, 0x80, v164
	v_add_u32_e32 v228, s46, v228
	v_lshlrev_b32_e32 v229, s1, v228
	v_and_b32_e32 v229, 0x3fff, v229
	v_ashrrev_i32_e32 v228, s10, v228
	v_add_u32_e32 v228, v229, v228
	v_ashrrev_i32_e32 v229, 31, v228
	v_lshl_add_u64 v[228:229], v[228:229], 4, v[162:163]
	v_lshl_add_u64 v[228:229], v[228:229], 3, s[18:19]
	global_load_dwordx4 v[224:227], v[228:229], off offset:16
	s_nop 0
	global_load_dwordx4 v[228:231], v[228:229], off
	v_add_u32_e32 v236, 0x90, v164
	v_add_u32_e32 v236, s46, v236
	v_lshlrev_b32_e32 v237, s1, v236
	v_and_b32_e32 v237, 0x3fff, v237
	v_ashrrev_i32_e32 v236, s10, v236
	v_add_u32_e32 v236, v237, v236
	v_ashrrev_i32_e32 v237, 31, v236
	v_lshl_add_u64 v[236:237], v[236:237], 4, v[162:163]
	v_lshl_add_u64 v[236:237], v[236:237], 3, s[18:19]
	global_load_dwordx4 v[232:235], v[236:237], off offset:16
	s_nop 0
	global_load_dwordx4 v[236:239], v[236:237], off
	s_waitcnt vmcnt(10)
	v_mov_b32_e32 v130, v192
	v_mov_b32_e32 v131, v193
	v_mov_b32_e32 v132, v194
	v_mov_b32_e32 v133, v195
	v_mov_b32_e32 v134, v196
	v_mov_b32_e32 v135, v197
	v_mov_b32_e32 v136, v198
	v_mov_b32_e32 v137, v199
	v_add_u32_e32 v196, 0xa0, v164
	v_add_u32_e32 v196, s46, v196
	v_lshlrev_b32_e32 v197, s1, v196
	v_and_b32_e32 v197, 0x3fff, v197
	v_ashrrev_i32_e32 v196, s10, v196
	v_add_u32_e32 v196, v197, v196
	v_ashrrev_i32_e32 v197, 31, v196
	v_lshl_add_u64 v[196:197], v[196:197], 4, v[162:163]
	v_lshl_add_u64 v[196:197], v[196:197], 3, s[18:19]
	global_load_dwordx4 v[192:195], v[196:197], off offset:16
	s_nop 0
	global_load_dwordx4 v[196:199], v[196:197], off
.LBB0_228:
	v_and_b32_e32 v165, 1, v165
	v_mov_b32_e32 v174, v124
	v_mov_b32_e32 v175, v120
	v_cmp_eq_u32_e32 vcc, 0, v165
	v_ashrrev_i32_e32 v165, 31, v164
	v_pk_mul_f32 v[174:175], v[174:175], v[134:135]
	v_lshlrev_b64 v[172:173], 12, v[164:165]
	v_sub_f32_e32 v165, v174, v175
	v_mov_b32_e32 v174, v120
	v_mov_b32_e32 v175, v124
	v_pk_mul_f32 v[174:175], v[174:175], v[134:135]
	v_mov_b32_e32 v120, v125
	v_mov_b32_e32 v124, v121
	v_add_f32_e32 v176, v175, v174
	v_pk_mul_f32 v[174:175], v[120:121], v[136:137]
	v_pk_mul_f32 v[120:121], v[124:125], v[136:137]
	s_mov_b32 s45, s61
	v_add_f32_e32 v124, v121, v120
	v_mov_b32_e32 v120, v126
	v_mov_b32_e32 v121, v122
	v_pk_mul_f32 v[120:121], v[120:121], v[130:131]
	s_lshl_b64 s[44:45], s[44:45], 1
	v_sub_f32_e32 v125, v120, v121
	v_mov_b32_e32 v120, v122
	v_mov_b32_e32 v121, v126
	v_pk_mul_f32 v[120:121], v[120:121], v[130:131]
	v_mov_b32_e32 v122, v127
	s_add_u32 s44, s11, s44
	v_sub_f32_e32 v174, v174, v175
	v_add_f32_e32 v175, v121, v120
	v_pk_mul_f32 v[120:121], v[122:123], v[132:133]
	v_mov_b32_e32 v126, v123
	v_add_u32_e32 v166, 12, v162
	s_addc_u32 s45, s12, s45
	v_sub_f32_e32 v122, v120, v121
	v_pk_mul_f32 v[120:121], v[126:127], v[132:133]
	v_cndmask_b32_e32 v166, v166, v162, vcc
	v_lshl_add_u64 v[172:173], s[44:45], 0, v[172:173]
	v_add_f32_e32 v123, v121, v120
	v_ashrrev_i32_e32 v167, 31, v166
	v_lshl_add_u64 v[172:173], v[172:173], 0, s[60:61]
	v_cvt_pk_bf16_f32 v120, v165, v174
	v_cvt_pk_bf16_f32 v121, v125, v122
	v_cvt_pk_bf16_f32 v122, v176, v124
	v_cvt_pk_bf16_f32 v123, v175, v123
	v_lshl_add_u64 v[172:173], v[166:167], 1, v[172:173]
	v_permlane16_swap_b32_e32 v120, v122
	v_permlane16_swap_b32_e32 v121, v123
; __device__ __forceinline__ unsigned cvt_pk_bf16(float lo, float hi) { unsigned r; asm volatile("v_cvt_pk_bf16_f32 %0, %1, %2" : "=v"(r) : "v"(lo), "v"(hi)); return r; }
;     __device__ __forceinline__ void operator()(const Acc& acc, const Unit& u, int wr, int wc, int fr, int fq) const {
;     ...
;                 if (wc == 0) { const f32x4* cp = csa + ((size_t)tok * 16 + 4 * fq) / 2; t0 = cp[0]; t1 = cp[1]; }
;                 bf16_t* rowp = O + u.coff + (size_t)row_in * D + wc * 32 + ((fq & 1) ? 16 + 4 * (fq - 1) : 4 * fq);
; #pragma unroll
;                 for (int bj = 0; bj < 2; ++bj) {
;                     const f32x4 x1 = acc[ai][bj][m][0], x2 = acc[ai][bj][m][1];
;                     float o1[4], o2[4];
;                     const float cc[4] = {t0[0], t0[2], t1[0], t1[2]}, ss[4] = {t0[1], t0[3], t1[1], t1[3]};
; #pragma unroll
;                     for (int j = 0; j < 4; ++j) { o1[j] = x1[j] * cc[j] - x2[j] * ss[j]; o2[j] = x2[j] * cc[j] + x1[j] * ss[j]; }
;                     const unsigned lo0 = cvt_pk_bf16(o1[0], o1[1]), lo1 = cvt_pk_bf16(o1[2], o1[3]), hi0 = cvt_pk_bf16(o2[0], o2[1]), hi1 = cvt_pk_bf16(o2[2], o2[3]);
;                     const auto s0 = __builtin_amdgcn_permlane16_swap(lo0, hi0, false, false), s1 = __builtin_amdgcn_permlane16_swap(lo1, hi1, false, false);
;                     *(u32x4*)(rowp + bj * HALF) = (u32x4){s0[0], s1[0], s0[1], s1[1]};
	global_store_dwordx4 v[172:173], v[120:123], off
	s_and_b64 vcc, exec, s[42:43]
	s_nop 0
	v_mov_b32_e32 v120, v116
	v_mov_b32_e32 v121, v112
	v_pk_mul_f32 v[120:121], v[120:121], v[134:135]
	s_nop 0
	v_sub_f32_e32 v122, v120, v121
	v_mov_b32_e32 v120, v112
	v_mov_b32_e32 v121, v116
	v_pk_mul_f32 v[120:121], v[120:121], v[134:135]
	v_mov_b32_e32 v112, v117
	v_mov_b32_e32 v116, v113
	v_add_f32_e32 v123, v121, v120
	v_pk_mul_f32 v[120:121], v[112:113], v[136:137]
	v_pk_mul_f32 v[112:113], v[116:117], v[136:137]
	v_sub_f32_e32 v120, v120, v121
	v_add_f32_e32 v116, v113, v112
	v_mov_b32_e32 v112, v118
	v_mov_b32_e32 v113, v114
	v_pk_mul_f32 v[112:113], v[112:113], v[130:131]
	s_nop 0
	v_sub_f32_e32 v117, v112, v113
	v_mov_b32_e32 v112, v114
	v_mov_b32_e32 v113, v118
	v_pk_mul_f32 v[112:113], v[112:113], v[130:131]
	v_mov_b32_e32 v114, v119
	v_add_f32_e32 v121, v113, v112
	v_pk_mul_f32 v[112:113], v[114:115], v[132:133]
	v_mov_b32_e32 v118, v115
	v_sub_f32_e32 v114, v112, v113
	v_pk_mul_f32 v[112:113], v[118:119], v[132:133]
	v_mov_b32_e32 v130, 1.0
	v_add_f32_e32 v115, v113, v112
	v_cvt_pk_bf16_f32 v112, v122, v120
	v_cvt_pk_bf16_f32 v113, v117, v114
	v_cvt_pk_bf16_f32 v114, v123, v116
	v_cvt_pk_bf16_f32 v115, v121, v115
	v_add_u32_e32 v116, 16, v164
	v_permlane16_swap_b32_e32 v112, v114
	v_permlane16_swap_b32_e32 v113, v115
	global_store_dwordx4 v[172:173], v[112:115], off offset:256
	v_mov_b32_e32 v131, 0
	s_nop 0
	v_mov_b32_e32 v112, 1.0
	v_mov_b32_e32 v113, 0
	v_mov_b32_e32 v114, 1.0
	v_mov_b32_e32 v115, 0
	s_cbranch_vccnz .LBB0_230
	s_waitcnt vmcnt(12)
	v_mov_b32_e32 v128, v200
	v_mov_b32_e32 v129, v201
	v_mov_b32_e32 v130, v202
	v_mov_b32_e32 v131, v203
	v_mov_b32_e32 v112, v204
	v_mov_b32_e32 v113, v205
	v_mov_b32_e32 v114, v206
	v_mov_b32_e32 v115, v207
	v_add_u32_e32 v204, 0xb0, v164
	v_add_u32_e32 v204, s46, v204
	v_lshlrev_b32_e32 v205, s1, v204
	v_and_b32_e32 v205, 0x3fff, v205
	v_ashrrev_i32_e32 v204, s10, v204
	v_add_u32_e32 v204, v205, v204
	v_ashrrev_i32_e32 v205, 31, v204
	v_lshl_add_u64 v[204:205], v[204:205], 4, v[162:163]
	v_lshl_add_u64 v[204:205], v[204:205], 3, s[18:19]
	global_load_dwordx4 v[200:203], v[204:205], off offset:16
	s_nop 0
	global_load_dwordx4 v[204:207], v[204:205], off
.LBB0_230:
	v_mov_b32_e32 v118, v108
	v_mov_b32_e32 v119, v104
	v_pk_mul_f32 v[118:119], v[118:119], v[112:113]
	v_ashrrev_i32_e32 v117, 31, v116
	v_sub_f32_e32 v120, v118, v119
	v_mov_b32_e32 v118, v104
	v_mov_b32_e32 v119, v108
	v_pk_mul_f32 v[118:119], v[118:119], v[112:113]
	v_mov_b32_e32 v104, v109
	v_mov_b32_e32 v108, v105
	v_add_f32_e32 v121, v119, v118
	v_pk_mul_f32 v[118:119], v[104:105], v[114:115]
	v_pk_mul_f32 v[104:105], v[108:109], v[114:115]
	v_sub_f32_e32 v118, v118, v119
	v_add_f32_e32 v108, v105, v104
	v_mov_b32_e32 v104, v110
	v_mov_b32_e32 v105, v106
	v_pk_mul_f32 v[104:105], v[104:105], v[128:129]
	v_lshlrev_b64 v[116:117], 12, v[116:117]
	v_sub_f32_e32 v109, v104, v105
	v_mov_b32_e32 v104, v106
	v_mov_b32_e32 v105, v110
	v_pk_mul_f32 v[104:105], v[104:105], v[128:129]
	v_mov_b32_e32 v106, v111
	v_add_f32_e32 v119, v105, v104
	v_pk_mul_f32 v[104:105], v[106:107], v[130:131]
	v_mov_b32_e32 v110, v107
	v_sub_f32_e32 v106, v104, v105
	v_pk_mul_f32 v[104:105], v[110:111], v[130:131]
	v_lshl_add_u64 v[116:117], s[44:45], 0, v[116:117]
	v_add_f32_e32 v107, v105, v104
	v_lshl_add_u64 v[116:117], v[116:117], 0, s[60:61]
	v_cvt_pk_bf16_f32 v104, v120, v118
	v_cvt_pk_bf16_f32 v105, v109, v106
	v_cvt_pk_bf16_f32 v106, v121, v108
	v_cvt_pk_bf16_f32 v107, v119, v107
	v_lshl_add_u64 v[116:117], v[166:167], 1, v[116:117]
	v_permlane16_swap_b32_e32 v104, v106
	v_permlane16_swap_b32_e32 v105, v107
	global_store_dwordx4 v[116:117], v[104:107], off
	s_and_b64 vcc, exec, s[42:43]
	s_nop 0
	v_mov_b32_e32 v104, v100
	v_mov_b32_e32 v105, v96
	v_pk_mul_f32 v[104:105], v[104:105], v[112:113]
	s_nop 0
	v_sub_f32_e32 v106, v104, v105
	v_mov_b32_e32 v104, v96
	v_mov_b32_e32 v105, v100
	v_pk_mul_f32 v[104:105], v[104:105], v[112:113]
	v_mov_b32_e32 v96, v101
	v_mov_b32_e32 v100, v97
	v_add_f32_e32 v107, v105, v104
	v_pk_mul_f32 v[104:105], v[96:97], v[114:115]
	v_pk_mul_f32 v[96:97], v[100:101], v[114:115]
	v_sub_f32_e32 v104, v104, v105
	v_add_f32_e32 v100, v97, v96
	v_mov_b32_e32 v96, v102
	v_mov_b32_e32 v97, v98
	v_pk_mul_f32 v[96:97], v[96:97], v[128:129]
	s_nop 0
	v_sub_f32_e32 v101, v96, v97
	v_mov_b32_e32 v96, v98
	v_mov_b32_e32 v97, v102
	v_pk_mul_f32 v[96:97], v[96:97], v[128:129]
	v_mov_b32_e32 v98, v103
	v_add_f32_e32 v105, v97, v96
	v_pk_mul_f32 v[96:97], v[98:99], v[130:131]
	v_mov_b32_e32 v102, v99
	v_sub_f32_e32 v98, v96, v97
	v_pk_mul_f32 v[96:97], v[102:103], v[130:131]
	v_mov_b32_e32 v102, 1.0
	v_add_f32_e32 v99, v97, v96
	v_cvt_pk_bf16_f32 v96, v106, v104
	v_cvt_pk_bf16_f32 v97, v101, v98
	v_cvt_pk_bf16_f32 v98, v107, v100
	v_cvt_pk_bf16_f32 v99, v105, v99
	v_add_u32_e32 v106, 32, v164
	v_permlane16_swap_b32_e32 v96, v98
	v_permlane16_swap_b32_e32 v97, v99
	global_store_dwordx4 v[116:117], v[96:99], off offset:256
	v_mov_b32_e32 v100, 1.0
	v_mov_b32_e32 v101, 0
	v_mov_b32_e32 v97, 0
	v_mov_b32_e32 v96, 1.0
	v_mov_b32_e32 v98, 1.0
	v_mov_b32_e32 v99, 0
	v_mov_b32_e32 v103, 0
	v_mov_b32_e32 v104, 1.0
	v_mov_b32_e32 v105, 0
	s_cbranch_vccnz .LBB0_232
	s_waitcnt vmcnt(14)
	v_mov_b32_e32 v98, v208
	v_mov_b32_e32 v99, v209
	v_mov_b32_e32 v100, v210
	v_mov_b32_e32 v101, v211
	v_mov_b32_e32 v102, v212
	v_mov_b32_e32 v103, v213
	v_mov_b32_e32 v104, v214
	v_mov_b32_e32 v105, v215
; __device__ __forceinline__ unsigned cvt_pk_bf16(float lo, float hi) { unsigned r; asm volatile("v_cvt_pk_bf16_f32 %0, %1, %2" : "=v"(r) : "v"(lo), "v"(hi)); return r; }
;     __device__ __forceinline__ void operator()(const Acc& acc, const Unit& u, int wr, int wc, int fr, int fq) const {
;     ...
;                 if (wc == 0) { const f32x4* cp = csa + ((size_t)tok * 16 + 4 * fq) / 2; t0 = cp[0]; t1 = cp[1]; }
;                 bf16_t* rowp = O + u.coff + (size_t)row_in * D + wc * 32 + ((fq & 1) ? 16 + 4 * (fq - 1) : 4 * fq);
; #pragma unroll
;                 for (int bj = 0; bj < 2; ++bj) {
;                     const f32x4 x1 = acc[ai][bj][m][0], x2 = acc[ai][bj][m][1];
;                     float o1[4], o2[4];
;                     const float cc[4] = {t0[0], t0[2], t1[0], t1[2]}, ss[4] = {t0[1], t0[3], t1[1], t1[3]};
; #pragma unroll
;                     for (int j = 0; j < 4; ++j) { o1[j] = x1[j] * cc[j] - x2[j] * ss[j]; o2[j] = x2[j] * cc[j] + x1[j] * ss[j]; }
;                     const unsigned lo0 = cvt_pk_bf16(o1[0], o1[1]), lo1 = cvt_pk_bf16(o1[2], o1[3]), hi0 = cvt_pk_bf16(o2[0], o2[1]), hi1 = cvt_pk_bf16(o2[2], o2[3]);
;                     const auto s0 = __builtin_amdgcn_permlane16_swap(lo0, hi0, false, false), s1 = __builtin_amdgcn_permlane16_swap(lo1, hi1, false, false);
;                     *(u32x4*)(rowp + bj * HALF) = (u32x4){s0[0], s1[0], s0[1], s1[1]};
.LBB0_232:
	v_mov_b32_e32 v108, v92
	v_mov_b32_e32 v109, v88
	v_pk_mul_f32 v[108:109], v[108:109], v[102:103]
	v_ashrrev_i32_e32 v107, 31, v106
	v_sub_f32_e32 v110, v108, v109
	v_mov_b32_e32 v108, v88
	v_mov_b32_e32 v109, v92
	v_pk_mul_f32 v[108:109], v[108:109], v[102:103]
	v_mov_b32_e32 v88, v93
	v_mov_b32_e32 v92, v89
	v_add_f32_e32 v111, v109, v108
	v_pk_mul_f32 v[108:109], v[88:89], v[104:105]
	v_pk_mul_f32 v[88:89], v[92:93], v[104:105]
	v_sub_f32_e32 v108, v108, v109
	v_add_f32_e32 v92, v89, v88
	v_mov_b32_e32 v88, v94
	v_mov_b32_e32 v89, v90
	v_pk_mul_f32 v[88:89], v[88:89], v[98:99]
	v_lshlrev_b64 v[106:107], 12, v[106:107]
	v_sub_f32_e32 v93, v88, v89
	v_mov_b32_e32 v88, v90
	v_mov_b32_e32 v89, v94
	v_pk_mul_f32 v[88:89], v[88:89], v[98:99]
	v_mov_b32_e32 v90, v95
	v_add_f32_e32 v109, v89, v88
	v_pk_mul_f32 v[88:89], v[90:91], v[100:101]
	v_mov_b32_e32 v94, v91
	v_sub_f32_e32 v90, v88, v89
	v_pk_mul_f32 v[88:89], v[94:95], v[100:101]
	v_lshl_add_u64 v[106:107], s[44:45], 0, v[106:107]
	v_add_f32_e32 v91, v89, v88
	v_lshl_add_u64 v[106:107], v[106:107], 0, s[60:61]
	v_cvt_pk_bf16_f32 v88, v110, v108
	v_cvt_pk_bf16_f32 v89, v93, v90
	v_cvt_pk_bf16_f32 v90, v111, v92
	v_cvt_pk_bf16_f32 v91, v109, v91
	v_lshl_add_u64 v[106:107], v[166:167], 1, v[106:107]
	v_permlane16_swap_b32_e32 v88, v90
	v_permlane16_swap_b32_e32 v89, v91
	global_store_dwordx4 v[106:107], v[88:91], off
	s_and_b64 vcc, exec, s[42:43]
	s_nop 0
	v_mov_b32_e32 v88, v84
	v_mov_b32_e32 v89, v80
	v_pk_mul_f32 v[88:89], v[88:89], v[102:103]
	s_nop 0
	v_sub_f32_e32 v90, v88, v89
	v_mov_b32_e32 v88, v80
	v_mov_b32_e32 v89, v84
	v_pk_mul_f32 v[88:89], v[88:89], v[102:103]
	v_mov_b32_e32 v80, v85
	v_mov_b32_e32 v84, v81
	v_add_f32_e32 v91, v89, v88
	v_pk_mul_f32 v[88:89], v[80:81], v[104:105]
	v_pk_mul_f32 v[80:81], v[84:85], v[104:105]
	v_sub_f32_e32 v88, v88, v89
	v_add_f32_e32 v84, v81, v80
	v_mov_b32_e32 v80, v86
	v_mov_b32_e32 v81, v82
	v_pk_mul_f32 v[80:81], v[80:81], v[98:99]
	s_nop 0
	v_sub_f32_e32 v85, v80, v81
	v_mov_b32_e32 v80, v82
	v_mov_b32_e32 v81, v86
	v_pk_mul_f32 v[80:81], v[80:81], v[98:99]
	v_mov_b32_e32 v82, v87
	v_add_f32_e32 v89, v81, v80
	v_pk_mul_f32 v[80:81], v[82:83], v[100:101]
	v_mov_b32_e32 v86, v83
	v_sub_f32_e32 v82, v80, v81
	v_pk_mul_f32 v[80:81], v[86:87], v[100:101]
	v_mov_b32_e32 v98, 1.0
	v_add_f32_e32 v83, v81, v80
	v_cvt_pk_bf16_f32 v80, v90, v88
	v_cvt_pk_bf16_f32 v81, v85, v82
	v_cvt_pk_bf16_f32 v82, v91, v84
	v_cvt_pk_bf16_f32 v83, v89, v83
	v_add_u32_e32 v84, 48, v164
	v_permlane16_swap_b32_e32 v80, v82
	v_permlane16_swap_b32_e32 v81, v83
	global_store_dwordx4 v[106:107], v[80:83], off offset:256
	v_mov_b32_e32 v99, 0
	s_nop 0
	v_mov_b32_e32 v80, 1.0
	v_mov_b32_e32 v81, 0
	v_mov_b32_e32 v82, 1.0
	v_mov_b32_e32 v83, 0
	s_cbranch_vccnz .LBB0_234
	s_waitcnt vmcnt(14)
	v_mov_b32_e32 v96, v216
	v_mov_b32_e32 v97, v217
	v_mov_b32_e32 v98, v218
	v_mov_b32_e32 v99, v219
	v_mov_b32_e32 v80, v220
	v_mov_b32_e32 v81, v221
	v_mov_b32_e32 v82, v222
	v_mov_b32_e32 v83, v223
.LBB0_234:
	v_mov_b32_e32 v86, v76
	v_mov_b32_e32 v87, v72
	v_pk_mul_f32 v[86:87], v[86:87], v[80:81]
	v_ashrrev_i32_e32 v85, 31, v84
	v_sub_f32_e32 v88, v86, v87
	v_mov_b32_e32 v86, v72
	v_mov_b32_e32 v87, v76
	v_pk_mul_f32 v[86:87], v[86:87], v[80:81]
	v_mov_b32_e32 v72, v77
	v_mov_b32_e32 v76, v73
	v_add_f32_e32 v89, v87, v86
	v_pk_mul_f32 v[86:87], v[72:73], v[82:83]
	v_pk_mul_f32 v[72:73], v[76:77], v[82:83]
	v_sub_f32_e32 v86, v86, v87
	v_add_f32_e32 v76, v73, v72
	v_mov_b32_e32 v72, v78
	v_mov_b32_e32 v73, v74
	v_pk_mul_f32 v[72:73], v[72:73], v[96:97]
	v_lshlrev_b64 v[84:85], 12, v[84:85]
	v_sub_f32_e32 v77, v72, v73
	v_mov_b32_e32 v72, v74
	v_mov_b32_e32 v73, v78
	v_pk_mul_f32 v[72:73], v[72:73], v[96:97]
	v_mov_b32_e32 v74, v79
	v_add_f32_e32 v87, v73, v72
	v_pk_mul_f32 v[72:73], v[74:75], v[98:99]
	v_mov_b32_e32 v78, v75
	v_sub_f32_e32 v74, v72, v73
	v_pk_mul_f32 v[72:73], v[78:79], v[98:99]
	v_lshl_add_u64 v[84:85], s[44:45], 0, v[84:85]
	v_add_f32_e32 v75, v73, v72
	v_lshl_add_u64 v[84:85], v[84:85], 0, s[60:61]
	v_cvt_pk_bf16_f32 v72, v88, v86
	v_cvt_pk_bf16_f32 v73, v77, v74
	v_cvt_pk_bf16_f32 v74, v89, v76
	v_cvt_pk_bf16_f32 v75, v87, v75
	v_lshl_add_u64 v[84:85], v[166:167], 1, v[84:85]
	v_permlane16_swap_b32_e32 v72, v74
	v_permlane16_swap_b32_e32 v73, v75
	global_store_dwordx4 v[84:85], v[72:75], off
	s_and_b64 vcc, exec, s[42:43]
	s_nop 0
	v_mov_b32_e32 v72, v68
	v_mov_b32_e32 v73, v64
	v_pk_mul_f32 v[72:73], v[72:73], v[80:81]
	s_nop 0
	v_sub_f32_e32 v74, v72, v73
	v_mov_b32_e32 v72, v64
	v_mov_b32_e32 v73, v68
	v_pk_mul_f32 v[72:73], v[72:73], v[80:81]
	v_mov_b32_e32 v64, v69
	v_mov_b32_e32 v68, v65
	v_add_f32_e32 v75, v73, v72
	v_pk_mul_f32 v[72:73], v[64:65], v[82:83]
	v_pk_mul_f32 v[64:65], v[68:69], v[82:83]
	v_sub_f32_e32 v72, v72, v73
	v_add_f32_e32 v68, v65, v64
	v_mov_b32_e32 v64, v70
	v_mov_b32_e32 v65, v66
	v_pk_mul_f32 v[64:65], v[64:65], v[96:97]
	s_nop 0
	v_sub_f32_e32 v69, v64, v65
	v_mov_b32_e32 v64, v66
	v_mov_b32_e32 v65, v70
	v_pk_mul_f32 v[64:65], v[64:65], v[96:97]
	v_mov_b32_e32 v66, v71
	v_add_f32_e32 v73, v65, v64
	v_pk_mul_f32 v[64:65], v[66:67], v[98:99]
	v_mov_b32_e32 v70, v67
	v_sub_f32_e32 v66, v64, v65
	v_pk_mul_f32 v[64:65], v[70:71], v[98:99]
	v_mov_b32_e32 v70, 1.0
	v_add_f32_e32 v67, v65, v64
	v_cvt_pk_bf16_f32 v64, v74, v72
	v_cvt_pk_bf16_f32 v65, v69, v66
	v_cvt_pk_bf16_f32 v66, v75, v68
	v_cvt_pk_bf16_f32 v67, v73, v67
	v_add_u32_e32 v74, 0x80, v164
	v_permlane16_swap_b32_e32 v64, v66
	v_permlane16_swap_b32_e32 v65, v67
	global_store_dwordx4 v[84:85], v[64:67], off offset:256
	v_mov_b32_e32 v68, 1.0
	v_mov_b32_e32 v69, 0
	v_mov_b32_e32 v65, 0
	v_mov_b32_e32 v64, 1.0
	v_mov_b32_e32 v66, 1.0
	v_mov_b32_e32 v67, 0
	v_mov_b32_e32 v71, 0
	v_mov_b32_e32 v72, 1.0
	v_mov_b32_e32 v73, 0
	s_cbranch_vccnz .LBB0_236
	s_waitcnt vmcnt(14)
	v_mov_b32_e32 v66, v224
	v_mov_b32_e32 v67, v225
	v_mov_b32_e32 v68, v226
	v_mov_b32_e32 v69, v227
	v_mov_b32_e32 v70, v228
	v_mov_b32_e32 v71, v229
	v_mov_b32_e32 v72, v230
	v_mov_b32_e32 v73, v231
; __device__ __forceinline__ unsigned cvt_pk_bf16(float lo, float hi) { unsigned r; asm volatile("v_cvt_pk_bf16_f32 %0, %1, %2" : "=v"(r) : "v"(lo), "v"(hi)); return r; }
;     __device__ __forceinline__ void operator()(const Acc& acc, const Unit& u, int wr, int wc, int fr, int fq) const {
;     ...
;                 if (wc == 0) { const f32x4* cp = csa + ((size_t)tok * 16 + 4 * fq) / 2; t0 = cp[0]; t1 = cp[1]; }
;                 bf16_t* rowp = O + u.coff + (size_t)row_in * D + wc * 32 + ((fq & 1) ? 16 + 4 * (fq - 1) : 4 * fq);
; #pragma unroll
;                 for (int bj = 0; bj < 2; ++bj) {
;                     const f32x4 x1 = acc[ai][bj][m][0], x2 = acc[ai][bj][m][1];
;                     float o1[4], o2[4];
;                     const float cc[4] = {t0[0], t0[2], t1[0], t1[2]}, ss[4] = {t0[1], t0[3], t1[1], t1[3]};
; #pragma unroll
;                     for (int j = 0; j < 4; ++j) { o1[j] = x1[j] * cc[j] - x2[j] * ss[j]; o2[j] = x2[j] * cc[j] + x1[j] * ss[j]; }
;                     const unsigned lo0 = cvt_pk_bf16(o1[0], o1[1]), lo1 = cvt_pk_bf16(o1[2], o1[3]), hi0 = cvt_pk_bf16(o2[0], o2[1]), hi1 = cvt_pk_bf16(o2[2], o2[3]);
;                     const auto s0 = __builtin_amdgcn_permlane16_swap(lo0, hi0, false, false), s1 = __builtin_amdgcn_permlane16_swap(lo1, hi1, false, false);
;                     *(u32x4*)(rowp + bj * HALF) = (u32x4){s0[0], s1[0], s0[1], s1[1]};
.LBB0_236:
	v_mov_b32_e32 v76, v60
	v_mov_b32_e32 v77, v56
	v_pk_mul_f32 v[76:77], v[76:77], v[70:71]
	v_ashrrev_i32_e32 v75, 31, v74
	v_sub_f32_e32 v78, v76, v77
	v_mov_b32_e32 v76, v56
	v_mov_b32_e32 v77, v60
	v_pk_mul_f32 v[76:77], v[76:77], v[70:71]
	v_mov_b32_e32 v56, v61
	v_mov_b32_e32 v60, v57
	v_add_f32_e32 v79, v77, v76
	v_pk_mul_f32 v[76:77], v[56:57], v[72:73]
	v_pk_mul_f32 v[56:57], v[60:61], v[72:73]
	v_sub_f32_e32 v76, v76, v77
	v_add_f32_e32 v60, v57, v56
	v_mov_b32_e32 v56, v62
	v_mov_b32_e32 v57, v58
	v_pk_mul_f32 v[56:57], v[56:57], v[66:67]
	v_lshlrev_b64 v[74:75], 12, v[74:75]
	v_sub_f32_e32 v61, v56, v57
	v_mov_b32_e32 v56, v58
	v_mov_b32_e32 v57, v62
	v_pk_mul_f32 v[56:57], v[56:57], v[66:67]
	v_mov_b32_e32 v58, v63
	v_add_f32_e32 v77, v57, v56
	v_pk_mul_f32 v[56:57], v[58:59], v[68:69]
	v_mov_b32_e32 v62, v59
	v_sub_f32_e32 v58, v56, v57
	v_pk_mul_f32 v[56:57], v[62:63], v[68:69]
	v_lshl_add_u64 v[74:75], s[44:45], 0, v[74:75]
	v_add_f32_e32 v59, v57, v56
	v_lshl_add_u64 v[74:75], v[74:75], 0, s[60:61]
	v_cvt_pk_bf16_f32 v56, v78, v76
	v_cvt_pk_bf16_f32 v57, v61, v58
	v_cvt_pk_bf16_f32 v58, v79, v60
	v_cvt_pk_bf16_f32 v59, v77, v59
	v_lshl_add_u64 v[74:75], v[166:167], 1, v[74:75]
	v_permlane16_swap_b32_e32 v56, v58
	v_permlane16_swap_b32_e32 v57, v59
	global_store_dwordx4 v[74:75], v[56:59], off
	s_and_b64 vcc, exec, s[42:43]
	s_nop 0
	v_mov_b32_e32 v56, v52
	v_mov_b32_e32 v57, v48
	v_pk_mul_f32 v[56:57], v[56:57], v[70:71]
	s_nop 0
	v_sub_f32_e32 v58, v56, v57
	v_mov_b32_e32 v56, v48
	v_mov_b32_e32 v57, v52
	v_pk_mul_f32 v[56:57], v[56:57], v[70:71]
	v_mov_b32_e32 v48, v53
	v_mov_b32_e32 v52, v49
	v_add_f32_e32 v59, v57, v56
	v_pk_mul_f32 v[56:57], v[48:49], v[72:73]
	v_pk_mul_f32 v[48:49], v[52:53], v[72:73]
	v_sub_f32_e32 v56, v56, v57
	v_add_f32_e32 v52, v49, v48
	v_mov_b32_e32 v48, v54
	v_mov_b32_e32 v49, v50
	v_pk_mul_f32 v[48:49], v[48:49], v[66:67]
	s_nop 0
	v_sub_f32_e32 v53, v48, v49
	v_mov_b32_e32 v48, v50
	v_mov_b32_e32 v49, v54
	v_pk_mul_f32 v[48:49], v[48:49], v[66:67]
	v_mov_b32_e32 v50, v55
	v_add_f32_e32 v57, v49, v48
	v_pk_mul_f32 v[48:49], v[50:51], v[68:69]
	v_mov_b32_e32 v54, v51
	v_sub_f32_e32 v50, v48, v49
	v_pk_mul_f32 v[48:49], v[54:55], v[68:69]
	v_mov_b32_e32 v66, 1.0
	v_add_f32_e32 v51, v49, v48
	v_cvt_pk_bf16_f32 v48, v58, v56
	v_cvt_pk_bf16_f32 v49, v53, v50
	v_cvt_pk_bf16_f32 v50, v59, v52
	v_cvt_pk_bf16_f32 v51, v57, v51
	v_add_u32_e32 v52, 0x90, v164
	v_permlane16_swap_b32_e32 v48, v50
	v_permlane16_swap_b32_e32 v49, v51
	global_store_dwordx4 v[74:75], v[48:51], off offset:256
	v_mov_b32_e32 v67, 0
	s_nop 0
	v_mov_b32_e32 v48, 1.0
	v_mov_b32_e32 v49, 0
	v_mov_b32_e32 v50, 1.0
	v_mov_b32_e32 v51, 0
	s_cbranch_vccnz .LBB0_238
	s_waitcnt vmcnt(14)
	v_mov_b32_e32 v64, v232
	v_mov_b32_e32 v65, v233
	v_mov_b32_e32 v66, v234
	v_mov_b32_e32 v67, v235
	v_mov_b32_e32 v48, v236
	v_mov_b32_e32 v49, v237
	v_mov_b32_e32 v50, v238
	v_mov_b32_e32 v51, v239
.LBB0_238:
	v_mov_b32_e32 v54, v44
	v_mov_b32_e32 v55, v40
	v_pk_mul_f32 v[54:55], v[54:55], v[48:49]
	v_ashrrev_i32_e32 v53, 31, v52
	v_sub_f32_e32 v56, v54, v55
	v_mov_b32_e32 v54, v40
	v_mov_b32_e32 v55, v44
	v_pk_mul_f32 v[54:55], v[54:55], v[48:49]
	v_mov_b32_e32 v40, v45
	v_mov_b32_e32 v44, v41
	v_add_f32_e32 v57, v55, v54
	v_pk_mul_f32 v[54:55], v[40:41], v[50:51]
	v_pk_mul_f32 v[40:41], v[44:45], v[50:51]
	v_sub_f32_e32 v54, v54, v55
	v_add_f32_e32 v44, v41, v40
	v_mov_b32_e32 v40, v46
	v_mov_b32_e32 v41, v42
	v_pk_mul_f32 v[40:41], v[40:41], v[64:65]
	v_lshlrev_b64 v[52:53], 12, v[52:53]
	v_sub_f32_e32 v45, v40, v41
	v_mov_b32_e32 v40, v42
	v_mov_b32_e32 v41, v46
	v_pk_mul_f32 v[40:41], v[40:41], v[64:65]
	v_mov_b32_e32 v42, v47
	v_add_f32_e32 v55, v41, v40
	v_pk_mul_f32 v[40:41], v[42:43], v[66:67]
	v_mov_b32_e32 v46, v43
	v_sub_f32_e32 v42, v40, v41
	v_pk_mul_f32 v[40:41], v[46:47], v[66:67]
	v_lshl_add_u64 v[52:53], s[44:45], 0, v[52:53]
	v_add_f32_e32 v43, v41, v40
	v_lshl_add_u64 v[52:53], v[52:53], 0, s[60:61]
	v_cvt_pk_bf16_f32 v40, v56, v54
	v_cvt_pk_bf16_f32 v41, v45, v42
	v_cvt_pk_bf16_f32 v42, v57, v44
	v_cvt_pk_bf16_f32 v43, v55, v43
	v_lshl_add_u64 v[52:53], v[166:167], 1, v[52:53]
	v_permlane16_swap_b32_e32 v40, v42
	v_permlane16_swap_b32_e32 v41, v43
	global_store_dwordx4 v[52:53], v[40:43], off
	s_and_b64 vcc, exec, s[42:43]
	s_nop 0
	v_mov_b32_e32 v40, v36
	v_mov_b32_e32 v41, v32
	v_pk_mul_f32 v[40:41], v[40:41], v[48:49]
	s_nop 0
	v_sub_f32_e32 v42, v40, v41
	v_mov_b32_e32 v40, v32
	v_mov_b32_e32 v41, v36
	v_pk_mul_f32 v[40:41], v[40:41], v[48:49]
	v_mov_b32_e32 v32, v37
	v_mov_b32_e32 v36, v33
	v_add_f32_e32 v43, v41, v40
	v_pk_mul_f32 v[40:41], v[32:33], v[50:51]
	v_pk_mul_f32 v[32:33], v[36:37], v[50:51]
	v_sub_f32_e32 v40, v40, v41
	v_add_f32_e32 v36, v33, v32
	v_mov_b32_e32 v32, v38
	v_mov_b32_e32 v33, v34
	v_pk_mul_f32 v[32:33], v[32:33], v[64:65]
	s_nop 0
	v_sub_f32_e32 v37, v32, v33
	v_mov_b32_e32 v32, v34
	v_mov_b32_e32 v33, v38
	v_pk_mul_f32 v[32:33], v[32:33], v[64:65]
	v_mov_b32_e32 v34, v39
	v_add_f32_e32 v41, v33, v32
	v_pk_mul_f32 v[32:33], v[34:35], v[66:67]
	v_mov_b32_e32 v38, v35
	v_sub_f32_e32 v34, v32, v33
	v_pk_mul_f32 v[32:33], v[38:39], v[66:67]
	v_mov_b32_e32 v38, 1.0
	v_add_f32_e32 v35, v33, v32
	v_cvt_pk_bf16_f32 v32, v42, v40
	v_cvt_pk_bf16_f32 v33, v37, v34
	v_cvt_pk_bf16_f32 v34, v43, v36
	v_cvt_pk_bf16_f32 v35, v41, v35
	v_add_u32_e32 v42, 0xa0, v164
	v_permlane16_swap_b32_e32 v32, v34
	v_permlane16_swap_b32_e32 v33, v35
	global_store_dwordx4 v[52:53], v[32:35], off offset:256
	v_mov_b32_e32 v36, 1.0
	v_mov_b32_e32 v37, 0
	v_mov_b32_e32 v33, 0
	v_mov_b32_e32 v32, 1.0
	v_mov_b32_e32 v34, 1.0
	v_mov_b32_e32 v35, 0
	v_mov_b32_e32 v39, 0
	v_mov_b32_e32 v40, 1.0
	v_mov_b32_e32 v41, 0
	s_cbranch_vccnz .LBB0_240
	s_waitcnt vmcnt(14)
	v_mov_b32_e32 v34, v192
	v_mov_b32_e32 v35, v193
	v_mov_b32_e32 v36, v194
	v_mov_b32_e32 v37, v195
	v_mov_b32_e32 v38, v196
	v_mov_b32_e32 v39, v197
	v_mov_b32_e32 v40, v198
	v_mov_b32_e32 v41, v199
; __device__ __forceinline__ unsigned cvt_pk_bf16(float lo, float hi) { unsigned r; asm volatile("v_cvt_pk_bf16_f32 %0, %1, %2" : "=v"(r) : "v"(lo), "v"(hi)); return r; }
;     __device__ __forceinline__ void operator()(const Acc& acc, const Unit& u, int wr, int wc, int fr, int fq) const {
;     ...
;                 if (wc == 0) { const f32x4* cp = csa + ((size_t)tok * 16 + 4 * fq) / 2; t0 = cp[0]; t1 = cp[1]; }
;                 bf16_t* rowp = O + u.coff + (size_t)row_in * D + wc * 32 + ((fq & 1) ? 16 + 4 * (fq - 1) : 4 * fq);
; #pragma unroll
;                 for (int bj = 0; bj < 2; ++bj) {
;                     const f32x4 x1 = acc[ai][bj][m][0], x2 = acc[ai][bj][m][1];
;                     float o1[4], o2[4];
;                     const float cc[4] = {t0[0], t0[2], t1[0], t1[2]}, ss[4] = {t0[1], t0[3], t1[1], t1[3]};
; #pragma unroll
;                     for (int j = 0; j < 4; ++j) { o1[j] = x1[j] * cc[j] - x2[j] * ss[j]; o2[j] = x2[j] * cc[j] + x1[j] * ss[j]; }
;                     const unsigned lo0 = cvt_pk_bf16(o1[0], o1[1]), lo1 = cvt_pk_bf16(o1[2], o1[3]), hi0 = cvt_pk_bf16(o2[0], o2[1]), hi1 = cvt_pk_bf16(o2[2], o2[3]);
;                     const auto s0 = __builtin_amdgcn_permlane16_swap(lo0, hi0, false, false), s1 = __builtin_amdgcn_permlane16_swap(lo1, hi1, false, false);
;                     *(u32x4*)(rowp + bj * HALF) = (u32x4){s0[0], s1[0], s0[1], s1[1]};
.LBB0_240:
	v_mov_b32_e32 v44, v28
	v_mov_b32_e32 v45, v24
	v_pk_mul_f32 v[44:45], v[44:45], v[38:39]
	v_ashrrev_i32_e32 v43, 31, v42
	v_sub_f32_e32 v46, v44, v45
	v_mov_b32_e32 v44, v24
	v_mov_b32_e32 v45, v28
	v_pk_mul_f32 v[44:45], v[44:45], v[38:39]
	v_mov_b32_e32 v24, v29
	v_mov_b32_e32 v28, v25
	v_add_f32_e32 v47, v45, v44
	v_pk_mul_f32 v[44:45], v[24:25], v[40:41]
	v_pk_mul_f32 v[24:25], v[28:29], v[40:41]
	v_sub_f32_e32 v44, v44, v45
	v_add_f32_e32 v28, v25, v24
	v_mov_b32_e32 v24, v30
	v_mov_b32_e32 v25, v26
	v_pk_mul_f32 v[24:25], v[24:25], v[34:35]
	v_lshlrev_b64 v[42:43], 12, v[42:43]
	v_sub_f32_e32 v29, v24, v25
	v_mov_b32_e32 v24, v26
	v_mov_b32_e32 v25, v30
	v_pk_mul_f32 v[24:25], v[24:25], v[34:35]
	v_mov_b32_e32 v26, v31
	v_add_f32_e32 v45, v25, v24
	v_pk_mul_f32 v[24:25], v[26:27], v[36:37]
	v_mov_b32_e32 v30, v27
	v_sub_f32_e32 v26, v24, v25
	v_pk_mul_f32 v[24:25], v[30:31], v[36:37]
	v_lshl_add_u64 v[42:43], s[44:45], 0, v[42:43]
	v_add_f32_e32 v27, v25, v24
	v_lshl_add_u64 v[42:43], v[42:43], 0, s[60:61]
	v_cvt_pk_bf16_f32 v24, v46, v44
	v_cvt_pk_bf16_f32 v25, v29, v26
	v_cvt_pk_bf16_f32 v26, v47, v28
	v_cvt_pk_bf16_f32 v27, v45, v27
	v_lshl_add_u64 v[42:43], v[166:167], 1, v[42:43]
	v_permlane16_swap_b32_e32 v24, v26
	v_permlane16_swap_b32_e32 v25, v27
	global_store_dwordx4 v[42:43], v[24:27], off
	s_and_b64 vcc, exec, s[42:43]
	s_nop 0
	v_mov_b32_e32 v24, v20
	v_mov_b32_e32 v25, v16
	v_pk_mul_f32 v[24:25], v[24:25], v[38:39]
	s_nop 0
	v_sub_f32_e32 v26, v24, v25
	v_mov_b32_e32 v24, v16
	v_mov_b32_e32 v25, v20
	v_pk_mul_f32 v[24:25], v[24:25], v[38:39]
	v_mov_b32_e32 v16, v21
	v_mov_b32_e32 v20, v17
	v_add_f32_e32 v27, v25, v24
	v_pk_mul_f32 v[24:25], v[16:17], v[40:41]
	v_pk_mul_f32 v[16:17], v[20:21], v[40:41]
	v_sub_f32_e32 v24, v24, v25
	v_add_f32_e32 v20, v17, v16
	v_mov_b32_e32 v16, v22
	v_mov_b32_e32 v17, v18
	v_pk_mul_f32 v[16:17], v[16:17], v[34:35]
	s_nop 0
	v_sub_f32_e32 v21, v16, v17
	v_mov_b32_e32 v16, v18
	v_mov_b32_e32 v17, v22
	v_pk_mul_f32 v[16:17], v[16:17], v[34:35]
	v_mov_b32_e32 v18, v23
	v_add_f32_e32 v25, v17, v16
	v_pk_mul_f32 v[16:17], v[18:19], v[36:37]
	v_mov_b32_e32 v22, v19
	v_sub_f32_e32 v18, v16, v17
	v_pk_mul_f32 v[16:17], v[22:23], v[36:37]
	v_mov_b32_e32 v34, 1.0
	v_add_f32_e32 v19, v17, v16
	v_cvt_pk_bf16_f32 v16, v26, v24
	v_cvt_pk_bf16_f32 v17, v21, v18
	v_cvt_pk_bf16_f32 v18, v27, v20
	v_cvt_pk_bf16_f32 v19, v25, v19
	v_add_u32_e32 v20, 0xb0, v164
	v_permlane16_swap_b32_e32 v16, v18
	v_permlane16_swap_b32_e32 v17, v19
	global_store_dwordx4 v[42:43], v[16:19], off offset:256
	v_mov_b32_e32 v35, 0
	s_nop 0
	v_mov_b32_e32 v16, 1.0
	v_mov_b32_e32 v17, 0
	v_mov_b32_e32 v18, 1.0
	v_mov_b32_e32 v19, 0
	s_cbranch_vccnz .LBB0_242
	s_waitcnt vmcnt(12)
	v_mov_b32_e32 v32, v200
	v_mov_b32_e32 v33, v201
	v_mov_b32_e32 v34, v202
	v_mov_b32_e32 v35, v203
	v_mov_b32_e32 v16, v204
	v_mov_b32_e32 v17, v205
	v_mov_b32_e32 v18, v206
	v_mov_b32_e32 v19, v207
.LBB0_242:
	v_mov_b32_e32 v22, v12
	v_mov_b32_e32 v23, v8
	v_pk_mul_f32 v[22:23], v[22:23], v[16:17]
	v_ashrrev_i32_e32 v21, 31, v20
	v_sub_f32_e32 v24, v22, v23
	v_mov_b32_e32 v22, v8
	v_mov_b32_e32 v23, v12
	v_pk_mul_f32 v[22:23], v[22:23], v[16:17]
	v_mov_b32_e32 v8, v13
	v_mov_b32_e32 v12, v9
	v_add_f32_e32 v25, v23, v22
	v_pk_mul_f32 v[22:23], v[8:9], v[18:19]
	v_pk_mul_f32 v[8:9], v[12:13], v[18:19]
	v_sub_f32_e32 v22, v22, v23
	v_add_f32_e32 v12, v9, v8
	v_mov_b32_e32 v8, v14
	v_mov_b32_e32 v9, v10
	v_pk_mul_f32 v[8:9], v[8:9], v[32:33]
	v_lshlrev_b64 v[20:21], 12, v[20:21]
	v_sub_f32_e32 v13, v8, v9
	v_mov_b32_e32 v8, v10
	v_mov_b32_e32 v9, v14
	v_pk_mul_f32 v[8:9], v[8:9], v[32:33]
	v_mov_b32_e32 v10, v15
	v_add_f32_e32 v23, v9, v8
	v_pk_mul_f32 v[8:9], v[10:11], v[34:35]
	v_mov_b32_e32 v14, v11
	v_sub_f32_e32 v10, v8, v9
	v_pk_mul_f32 v[8:9], v[14:15], v[34:35]
	v_lshl_add_u64 v[20:21], s[44:45], 0, v[20:21]
	v_add_f32_e32 v11, v9, v8
	v_lshl_add_u64 v[20:21], v[20:21], 0, s[60:61]
	v_cvt_pk_bf16_f32 v8, v24, v22
	v_cvt_pk_bf16_f32 v9, v13, v10
	v_cvt_pk_bf16_f32 v10, v25, v12
	v_cvt_pk_bf16_f32 v11, v23, v11
	v_lshl_add_u64 v[20:21], v[166:167], 1, v[20:21]
	v_permlane16_swap_b32_e32 v8, v10
	v_permlane16_swap_b32_e32 v9, v11
	global_store_dwordx4 v[20:21], v[8:11], off
	s_andn2_b64 vcc, exec, s[40:41]
	s_mov_b64 s[40:41], -1
	v_mov_b32_e32 v8, v4
	v_mov_b32_e32 v9, v0
	v_pk_mul_f32 v[8:9], v[8:9], v[16:17]
	s_nop 0
	v_sub_f32_e32 v10, v8, v9
	v_mov_b32_e32 v8, v0
	v_mov_b32_e32 v9, v4
	v_pk_mul_f32 v[8:9], v[8:9], v[16:17]
	v_mov_b32_e32 v0, v5
	v_mov_b32_e32 v4, v1
	v_add_f32_e32 v11, v9, v8
	v_pk_mul_f32 v[8:9], v[0:1], v[18:19]
	v_pk_mul_f32 v[0:1], v[4:5], v[18:19]
	v_sub_f32_e32 v8, v8, v9
	v_add_f32_e32 v4, v1, v0
	v_mov_b32_e32 v0, v6
	v_mov_b32_e32 v1, v2
	v_pk_mul_f32 v[0:1], v[0:1], v[32:33]
	s_nop 0
	v_sub_f32_e32 v5, v0, v1
	v_mov_b32_e32 v0, v2
	v_mov_b32_e32 v1, v6
	v_pk_mul_f32 v[0:1], v[0:1], v[32:33]
	v_mov_b32_e32 v2, v7
	v_add_f32_e32 v9, v1, v0
	v_pk_mul_f32 v[0:1], v[2:3], v[34:35]
	v_mov_b32_e32 v6, v3
	v_sub_f32_e32 v2, v0, v1
	v_pk_mul_f32 v[0:1], v[6:7], v[34:35]
	s_nop 0
	v_add_f32_e32 v3, v1, v0
	v_cvt_pk_bf16_f32 v0, v10, v8
	v_cvt_pk_bf16_f32 v1, v5, v2
	v_cvt_pk_bf16_f32 v2, v11, v4
	v_cvt_pk_bf16_f32 v3, v9, v3
	s_nop 0
	v_permlane16_swap_b32_e32 v0, v2
	v_permlane16_swap_b32_e32 v1, v3
	global_store_dwordx4 v[20:21], v[0:3], off offset:256
	s_cbranch_vccnz .LBB0_215
	s_andn2_b64 vcc, exec, s[24:25]
	s_cbranch_vccnz .LBB0_214
	s_barrier
	s_branch .LBB0_214
